# attention tile loop: hot branch targets aligned to 32 B with never-executed padding; code after phase 5 pinned at its previous placement
# baseline (speedup 1.0000x reference)
.Lcf_rare_a:
	v_add_f32_e32 v221, v218, v220
	v_add_f32_e32 v221, 0x40800000, v221
	v_and_b32_e32 v222, 0xffff0000, v221
	v_cmp_lt_f32_e32 vcc, v222, v221
	v_add_u32_e32 v223, 0x10000, v222
	s_nop 0
	v_cndmask_b32_e32 v222, v222, v223, vcc
	v_max_f32_e32 v223, v218, v222
	s_cmp_eq_u32 s26, 0
	s_cselect_b64 vcc, -1, 0
	s_nop 1
	v_cndmask_b32_e32 v222, v223, v222, vcc
	v_sub_f32_e32 v223, v218, v222
	v_exp_f32_e32 v224, v223
	v_add_f32_e32 v112, v223, v112
	v_add_f32_e32 v113, v223, v113
	v_add_f32_e32 v114, v223, v114
	v_add_f32_e32 v115, v223, v115
	v_add_f32_e32 v116, v223, v116
	v_add_f32_e32 v117, v223, v117
	v_add_f32_e32 v118, v223, v118
	v_add_f32_e32 v119, v223, v119
	v_add_f32_e32 v120, v223, v120
	v_add_f32_e32 v121, v223, v121
	v_add_f32_e32 v122, v223, v122
	v_add_f32_e32 v123, v223, v123
	v_add_f32_e32 v124, v223, v124
	v_add_f32_e32 v125, v223, v125
	v_add_f32_e32 v126, v223, v126
	v_add_f32_e32 v127, v223, v127
	v_add_f32_e32 v80, v223, v80
	v_add_f32_e32 v81, v223, v81
	v_add_f32_e32 v82, v223, v82
	v_add_f32_e32 v83, v223, v83
	v_add_f32_e32 v84, v223, v84
	v_add_f32_e32 v85, v223, v85
	v_add_f32_e32 v86, v223, v86
	v_add_f32_e32 v87, v223, v87
	v_add_f32_e32 v88, v223, v88
	v_add_f32_e32 v89, v223, v89
	v_add_f32_e32 v90, v223, v90
	v_add_f32_e32 v91, v223, v91
	v_add_f32_e32 v92, v223, v92
	v_add_f32_e32 v93, v223, v93
	v_add_f32_e32 v94, v223, v94
	v_add_f32_e32 v95, v223, v95
	v_mov_b32_e32 v218, v222
	v_xor_b32_e32 v223, 0x80000000, v222
	v_cmp_ne_u32_e32 vcc, 0, v244
	v_lshrrev_b32_e32 v223, 16, v223
	s_nop 1
	v_cndmask_b32_e32 v248, 0, v223, vcc
	s_cmp_eq_u32 s26, 0
	s_cbranch_scc1 .LBB0_1255
	v_pk_mul_f32 v[62:63], v[62:63], v[224:225] op_sel_hi:[1,0]
	v_pk_mul_f32 v[60:61], v[60:61], v[224:225] op_sel_hi:[1,0]
	v_pk_mul_f32 v[58:59], v[58:59], v[224:225] op_sel_hi:[1,0]
	v_pk_mul_f32 v[56:57], v[56:57], v[224:225] op_sel_hi:[1,0]
	v_pk_mul_f32 v[54:55], v[54:55], v[224:225] op_sel_hi:[1,0]
	v_pk_mul_f32 v[52:53], v[52:53], v[224:225] op_sel_hi:[1,0]
	v_pk_mul_f32 v[50:51], v[50:51], v[224:225] op_sel_hi:[1,0]
	v_pk_mul_f32 v[48:49], v[48:49], v[224:225] op_sel_hi:[1,0]
	v_pk_mul_f32 v[46:47], v[46:47], v[224:225] op_sel_hi:[1,0]
	v_pk_mul_f32 v[44:45], v[44:45], v[224:225] op_sel_hi:[1,0]
	v_pk_mul_f32 v[42:43], v[42:43], v[224:225] op_sel_hi:[1,0]
	v_pk_mul_f32 v[40:41], v[40:41], v[224:225] op_sel_hi:[1,0]
	v_pk_mul_f32 v[38:39], v[38:39], v[224:225] op_sel_hi:[1,0]
	v_pk_mul_f32 v[36:37], v[36:37], v[224:225] op_sel_hi:[1,0]
	v_pk_mul_f32 v[34:35], v[34:35], v[224:225] op_sel_hi:[1,0]
	v_pk_mul_f32 v[32:33], v[32:33], v[224:225] op_sel_hi:[1,0]
	v_mul_f32_e32 v212, v212, v224
	.p2align 5

; #define TLOAD(kt) do { const int key0 = (kt) * 64; \
;     rk = *(const uint4*)(KN + (size_t)(key0 + (tid >> 3)) * 64 + (tid & 7) * 8); \
;     if (tid < 256) rr = *(const uint4*)(KR + (size_t)(key0 + (tid >> 2)) * 32 + (tid & 3) * 8); \
;     rv = *(const uint4*)(VT + (size_t)(tid >> 3) * LK + key0 + (tid & 7) * 8); } while (0)
; #define TSTORE(st) do { bf16_t* Ks = Kl + (st) * KB; \
;     *(uint4*)(Ks + (tid >> 3) * AK_LD + (tid & 7) * 8) = rk; \
;     if (tid < 256) *(uint4*)(Ks + (tid >> 2) * AK_LD + 64 + (tid & 3) * 8) = rr; \
;     *(uint4*)(Vl + (st) * VB + (tid >> 3) * AV_LD + (tid & 7) * 8) = rv; } while (0)
; #define QKSTEP(off, qa, qbb) do { const bf16x8 a0 = *(const bf16x8*)(kp + (off)), a1 = *(const bf16x8*)(kp + 32 * AK_LD + (off)); \
;       s00 = MF(a0, qa, s00); s01 = MF(a1, qa, s01); s10 = MF(a0, qbb, s10); s11 = MF(a1, qbb, s11); } while (0)
; #define PVSTEP(sx, sy, o, koff) do { union { uint4 u; bf16x8 v; } p0, p1; p0.u = PK8(sx, o); p1.u = PK8(sy, o); \
;       const bf16x8 v0 = *(const bf16x8*)(vp + (koff)), v1 = *(const bf16x8*)(vp + 32 * AV_LD + (koff)); \
;       O00 = MF(v0, p0.v, O00); O01 = MF(v1, p0.v, O01); O10 = MF(v0, p1.v, O10); O11 = MF(v1, p1.v, O11); } while (0)
; DI void attn_item(const Params& P, int item, unsigned char* lds) {
;     ...
;   const int NKT = LK / 64;
;   __syncthreads();
;   TLOAD(0); TSTORE(0);
;   __syncthreads();
;   for (int kt = 0; kt < NKT; ++kt) {
;     { const int k1 = (kt + 1 < NKT) ? kt + 1 : NKT - 1; TLOAD(k1); }
;     const bf16_t* Ks = Kl + (kt & 1) * KB; const bf16_t* Vs = Vl + (kt & 1) * VB;
;     f32x16 s00, s01, s10, s11;
; #pragma unroll
;     for (int e = 0; e < 16; ++e) { s00[e] = 0.f; s01[e] = 0.f; s10[e] = 0.f; s11[e] = 0.f; }
;     const bf16_t* kp = Ks + l31 * AK_LD + hh * 8;
;     ...
;     QKSTEP(0, qa0, qb0); QKSTEP(16, qa1, qb1); QKSTEP(32, qa2, qb2); QKSTEP(48, qa3, qb3); QKSTEP(64, qa4, qb4); QKSTEP(80, qa5, qb5);
;     ...
;     SOFTMAX(s00, s01, m0, l0, O00, O01);
;     SOFTMAX(s10, s11, m1, l1, O10, O11);
;     const bf16_t* vp = Vs + l31 * AV_LD + 8 * hh;
;     ...
;     PVSTEP(s00, s10, 0, 0); PVSTEP(s00, s10, 8, 16); PVSTEP(s01, s11, 0, 32); PVSTEP(s01, s11, 8, 48);
;     ...
;     TSTORE((kt + 1) & 1);
;     __syncthreads();
.LBB0_1265:
	v_sub_f32_e32 v80, v80, v218
	v_exp_f32_e32 v132, v80
	v_sub_f32_e32 v80, v113, v218
	v_exp_f32_e32 v135, v80
	v_sub_f32_e32 v80, v81, v218
	v_exp_f32_e32 v134, v80
	v_sub_f32_e32 v80, v114, v218
	v_exp_f32_e32 v137, v80
	v_sub_f32_e32 v80, v82, v218
	v_exp_f32_e32 v136, v80
	v_sub_f32_e32 v80, v115, v218
	v_exp_f32_e32 v115, v80
	v_sub_f32_e32 v80, v83, v218
	v_exp_f32_e32 v114, v80
	v_sub_f32_e32 v80, v116, v218
	v_exp_f32_e32 v139, v80
	v_sub_f32_e32 v80, v84, v218
	v_exp_f32_e32 v138, v80
	v_sub_f32_e32 v80, v117, v218
	v_exp_f32_e32 v117, v80
	v_sub_f32_e32 v80, v85, v218
	v_exp_f32_e32 v116, v80
	v_sub_f32_e32 v80, v118, v218
	v_exp_f32_e32 v141, v80
	v_sub_f32_e32 v80, v86, v218
	v_exp_f32_e32 v140, v80
	v_sub_f32_e32 v80, v119, v218
	v_exp_f32_e32 v119, v80
	v_sub_f32_e32 v80, v87, v218
	v_exp_f32_e32 v118, v80
	v_sub_f32_e32 v80, v120, v218
	v_exp_f32_e32 v143, v80
	v_sub_f32_e32 v80, v88, v218
	v_exp_f32_e32 v142, v80
	v_sub_f32_e32 v80, v121, v218
	v_exp_f32_e32 v121, v80
	v_sub_f32_e32 v80, v89, v218
	v_exp_f32_e32 v120, v80
	v_sub_f32_e32 v80, v122, v218
	v_exp_f32_e32 v145, v80
	v_sub_f32_e32 v80, v90, v218
	v_exp_f32_e32 v144, v80
	v_sub_f32_e32 v80, v123, v218
	v_exp_f32_e32 v123, v80
	v_sub_f32_e32 v80, v91, v218
	v_exp_f32_e32 v122, v80
	v_sub_f32_e32 v80, v124, v218
	v_exp_f32_e32 v147, v80
	v_sub_f32_e32 v80, v92, v218
	v_exp_f32_e32 v146, v80
	v_sub_f32_e32 v80, v125, v218
	v_exp_f32_e32 v125, v80
	v_sub_f32_e32 v80, v93, v218
	ds_read_b128 v[152:155], v216 offset:35840
	v_exp_f32_e32 v124, v80
	v_sub_f32_e32 v80, v96, v217
	v_exp_f32_e32 v81, v80
	v_sub_f32_e32 v80, v97, v217
	v_sub_f32_e32 v112, v112, v218
	v_exp_f32_e32 v83, v80
	v_sub_f32_e32 v80, v98, v217
	v_exp_f32_e32 v133, v112
	v_exp_f32_e32 v85, v80
	v_sub_f32_e32 v80, v99, v217
	ds_read_b128 v[156:159], v216 offset:40448
	ds_read_b128 v[160:163], v216 offset:35872
	v_exp_f32_e32 v87, v80
	v_sub_f32_e32 v80, v100, v217
	v_exp_f32_e32 v89, v80
	v_sub_f32_e32 v80, v101, v217
	v_exp_f32_e32 v91, v80
	v_sub_f32_e32 v80, v102, v217
	v_cvt_pk_bf16_f32 v96, v133, v135
	v_cvt_pk_bf16_f32 v97, v137, v115
	v_cvt_pk_bf16_f32 v98, v139, v117
	v_cvt_pk_bf16_f32 v99, v141, v119
	v_exp_f32_e32 v93, v80
	v_sub_f32_e32 v80, v103, v217
	s_waitcnt lgkmcnt(2)
	v_mfma_f32_32x32x16_bf16 v[48:63], v[152:155], v[96:99], v[48:63]
	v_cvt_pk_bf16_f32 v100, v81, v83
	v_cvt_pk_bf16_f32 v101, v85, v87
	v_cvt_pk_bf16_f32 v102, v89, v91
	ds_read_b128 v[164:167], v216 offset:40480
	v_sub_f32_e32 v64, v64, v217
	v_sub_f32_e32 v68, v68, v217
	v_sub_f32_e32 v86, v67, v217
	s_waitcnt lgkmcnt(2)
	v_mfma_f32_32x32x16_bf16 v[32:47], v[156:159], v[96:99], v[32:47]
	v_exp_f32_e32 v97, v80
	v_sub_f32_e32 v80, v126, v218
	v_cvt_pk_bf16_f32 v67, v140, v118
	v_exp_f32_e32 v88, v68
	v_cvt_pk_bf16_f32 v103, v93, v97
	v_sub_f32_e32 v68, v69, v217
	v_exp_f32_e32 v90, v68
	v_mfma_f32_32x32x16_bf16 v[16:31], v[152:155], v[100:103], v[16:31]
	v_exp_f32_e32 v153, v80
	v_sub_f32_e32 v80, v127, v218
	v_exp_f32_e32 v127, v80
	v_sub_f32_e32 v80, v104, v217
	v_exp_f32_e32 v99, v80
	v_sub_f32_e32 v80, v105, v217
	v_cvt_pk_bf16_f32 v154, v143, v121
	v_mfma_f32_32x32x16_bf16 v[0:15], v[156:159], v[100:103], v[0:15]
	v_exp_f32_e32 v101, v80
	v_sub_f32_e32 v80, v106, v217
	v_exp_f32_e32 v103, v80
	v_sub_f32_e32 v80, v107, v217
	v_exp_f32_e32 v105, v80
	v_sub_f32_e32 v80, v108, v217
	v_exp_f32_e32 v107, v80
	v_sub_f32_e32 v80, v109, v217
	v_exp_f32_e32 v109, v80
	v_sub_f32_e32 v80, v110, v217
	v_exp_f32_e32 v113, v80
	v_sub_f32_e32 v80, v111, v217
	v_exp_f32_e32 v111, v80
	v_cvt_pk_bf16_f32 v155, v145, v123
	v_cvt_pk_bf16_f32 v156, v147, v125
	v_cvt_pk_bf16_f32 v157, v153, v127
	v_exp_f32_e32 v80, v64
	v_sub_f32_e32 v64, v65, v217
	s_waitcnt lgkmcnt(1)
	v_mfma_f32_32x32x16_bf16 v[48:63], v[160:163], v[154:157], v[48:63]
	v_exp_f32_e32 v82, v64
	v_sub_f32_e32 v64, v66, v217
	v_exp_f32_e32 v84, v64
	v_cvt_pk_bf16_f32 v64, v132, v134
	v_cvt_pk_bf16_f32 v65, v136, v114
	v_cvt_pk_bf16_f32 v66, v138, v116
	v_sub_f32_e32 v68, v70, v217
	s_waitcnt lgkmcnt(0)
	v_mfma_f32_32x32x16_bf16 v[32:47], v[164:167], v[154:157], v[32:47]
	v_cvt_pk_bf16_f32 v154, v99, v101
	v_cvt_pk_bf16_f32 v155, v103, v105
	v_cvt_pk_bf16_f32 v156, v107, v109
	v_cvt_pk_bf16_f32 v157, v113, v111
	v_exp_f32_e32 v86, v86
	v_exp_f32_e32 v92, v68
	v_sub_f32_e32 v68, v94, v218
	v_mfma_f32_32x32x16_bf16 v[16:31], v[160:163], v[154:157], v[16:31]
	ds_read_b128 v[158:161], v216 offset:35904
	v_exp_f32_e32 v152, v68
	v_sub_f32_e32 v68, v95, v218
	v_exp_f32_e32 v126, v68
	v_sub_f32_e32 v68, v72, v217
	v_exp_f32_e32 v98, v68
	v_sub_f32_e32 v68, v73, v217
	v_mfma_f32_32x32x16_bf16 v[0:15], v[164:167], v[154:157], v[0:15]
	ds_read_b128 v[154:157], v216 offset:40512
	ds_read_b128 v[162:165], v216 offset:35936
	ds_read_b128 v[166:169], v216 offset:40544
	v_exp_f32_e32 v100, v68
	v_sub_f32_e32 v68, v75, v217
	v_exp_f32_e32 v104, v68
	v_sub_f32_e32 v68, v76, v217
	v_exp_f32_e32 v106, v68
	s_waitcnt lgkmcnt(3)
	v_mfma_f32_32x32x16_bf16 v[48:63], v[158:161], v[64:67], v[48:63]
	v_sub_f32_e32 v68, v77, v217
	v_exp_f32_e32 v108, v68
	v_sub_f32_e32 v68, v78, v217
	v_exp_f32_e32 v112, v68
	s_waitcnt vmcnt(1)
	ds_write_b128 v214, v[180:183]
	s_waitcnt lgkmcnt(3)
	v_mfma_f32_32x32x16_bf16 v[32:47], v[154:157], v[64:67], v[32:47]
	v_sub_f32_e32 v64, v71, v217
	v_exp_f32_e32 v96, v64
	v_cvt_pk_bf16_f32 v64, v80, v82
	v_cvt_pk_bf16_f32 v65, v84, v86
	v_cvt_pk_bf16_f32 v66, v88, v90
	v_cvt_pk_bf16_f32 v67, v92, v96
	s_nop 1
	v_mfma_f32_32x32x16_bf16 v[16:31], v[158:161], v[64:67], v[16:31]
	v_mfma_f32_32x32x16_bf16 v[0:15], v[154:157], v[64:67], v[0:15]
	v_sub_f32_e32 v64, v74, v217
	v_exp_f32_e32 v102, v64
	v_cvt_pk_bf16_f32 v64, v142, v120
	v_cvt_pk_bf16_f32 v65, v144, v122
	v_cvt_pk_bf16_f32 v66, v146, v124
	v_cvt_pk_bf16_f32 v67, v152, v126
	s_waitcnt lgkmcnt(2)
	s_nop 0
	v_mfma_f32_32x32x16_bf16 v[48:63], v[162:165], v[64:67], v[48:63]
	s_waitcnt lgkmcnt(1)
	v_mfma_f32_32x32x16_bf16 v[32:47], v[166:169], v[64:67], v[32:47]
	v_sub_f32_e32 v64, v79, v217
	v_exp_f32_e32 v110, v64
	v_cvt_pk_bf16_f32 v64, v98, v100
	v_cvt_pk_bf16_f32 v65, v102, v104
	v_cvt_pk_bf16_f32 v66, v106, v108
	v_cvt_pk_bf16_f32 v67, v112, v110
	s_nop 1
	v_mfma_f32_32x32x16_bf16 v[16:31], v[162:165], v[64:67], v[16:31]
	v_mfma_f32_32x32x16_bf16 v[0:15], v[166:169], v[64:67], v[0:15]
	s_and_saveexec_b64 s[20:21], s[4:5]
	s_cbranch_execz .LBB0_1236
	v_lshl_add_u32 v64, v194, 1, v215
	ds_write_b128 v64, v[128:131] offset:128
	s_branch .LBB0_1236
	.p2align 6
	s_nop 0
	s_nop 0
	s_nop 0
	s_nop 0
	s_nop 0
	s_nop 0
	s_nop 0
	s_nop 0
	s_nop 0
	s_nop 0
